# t38 + attention QK phase issues all 8 K-fragment LDS reads up front with counted lgkmcnt waits (3 step variants); pad trimmed so downstream layout is byte-identical
# baseline (speedup 1.0000x reference)
; #define LAS __attribute__((address_space(3)))
; #define MFMA32(a, b, c) __builtin_amdgcn_mfma_f32_32x32x16_bf16((a), (b), (c), 0, 0, 0)
; #define WG_BAR() do { asm volatile("s_waitcnt lgkmcnt(0)" ::: "memory"); __builtin_amdgcn_s_barrier(); asm volatile("" ::: "memory"); } while (0)
; template <class ScoreFn>
; __device__ __forceinline__ void attn_step(AttnState& st, const bf16x8 (&qf)[4], LAS unsigned char* kb, LAS unsigned char* vb, int lane, const ScoreFn& sf) {
;     ...
;     LAS unsigned char* kp = kb + r * KVP; const int kx = (h ^ (r & 7)) << 4;
; #pragma unroll
;     for (int ds = 0; ds < 4; ++ds) {
;         const bf16x8 k0 = *(const LAS bf16x8*)(kp + (kx ^ (ds << 5))), k1 = *(const LAS bf16x8*)(kp + 32 * KVP + (kx ^ (ds << 5)));
;         s0 = MFMA32(k0, qf[ds], s0); s1 = MFMA32(k1, qf[ds], s1);
;     }
;     float mt = NEG_BIG;
;     __builtin_amdgcn_sched_barrier(0);
; #pragma unroll
;     for (int i = 0; i < 16; ++i) { s0[i] = sf(s0[i], (i & 3) + 8 * (i >> 2), h, r); mt = fmaxf(mt, s0[i]); if ((i & 7) == 7) __builtin_amdgcn_sched_barrier(0); }
; #pragma unroll
;     for (int i = 0; i < 16; ++i) { s1[i] = sf(s1[i], 32 + (i & 3) + 8 * (i >> 2), h, r); mt = fmaxf(mt, s1[i]); if ((i & 7) == 7) __builtin_amdgcn_sched_barrier(0); }
;     mt = fmaxf(mt, __shfl_xor(mt, 32));
;     const float mn = fmaxf(st.m, mt), alpha = __builtin_amdgcn_exp2f(st.m - mn);
;     float ps = 0.f;
; #pragma unroll
;     for (int i = 0; i < 16; ++i) { s0[i] = __builtin_amdgcn_exp2f(s0[i] - mn); s1[i] = __builtin_amdgcn_exp2f(s1[i] - mn); ps += s0[i] + s1[i]; }
; template <bool ISB>
; __device__ __forceinline__ void attn_wg_item(Frame& F, int l, int idx) {
;     ...
;     AttnState st;
; #pragma unroll
;     for (int i = 0; i < 16; ++i) { st.o0[i] = 0.f; st.o1[i] = 0.f; }
;     st.m = NEG_BIG; st.l = 0.f;
; #pragma unroll
;     for (int t = 0; t < ATT_D; ++t) ATT_DMA(t);
;     if (ISB && lat) {
;         const float* bsrc = KIN(I_NBBIAS) + (size_t)(l * 8 + (ix & 7)) * 465;
;         if (tid < 465) tab[64 + tid] = bsrc[tid] * LOG2E; }
;     for (int s = 0; s < NS; ++s) {
;         ATT_DMA(s + ATT_D);
;         asm volatile("s_waitcnt vmcnt(8)" ::: "memory");
;         WG_BAR();
;         LAS unsigned char* cur = ring + (s % ATT_NB) * KV_BUF;
.LBB0_581:
	s_mul_hi_u32 s1, s16, 0xaaaaaaab
	s_mul_hi_u32 s2, s13, 0xaaaaaaab
	s_lshr_b32 s1, s1, 2
	s_lshr_b32 s2, s2, 2
	s_mul_i32 s1, s1, 0x18000
	s_mul_i32 s2, s2, 0x18000
	v_readlane_b32 s3, v253, 15
	s_sub_i32 s1, s15, s1
	v_add3_u32 v126, s1, v104, v89
	v_add3_u32 v125, s1, v96, v89
	v_add3_u32 v127, s1, v103, v89
	v_add3_u32 v124, s1, v95, v89
	v_add3_u32 v122, s1, v102, v89
	v_add3_u32 v123, s1, v101, v89
	v_add3_u32 v119, s1, v94, v89
	v_add3_u32 v120, s1, v93, v89
	v_add3_u32 v117, s1, v100, v89
	v_add3_u32 v118, s1, v99, v89
	v_add3_u32 v115, s1, v92, v89
	v_add3_u32 v116, s1, v91, v89
	v_add3_u32 v113, s1, v98, v89
	v_add3_u32 v114, s1, v97, v89
	v_add3_u32 v111, s1, v90, v89
	v_add3_u32 v112, s1, v88, v89
	v_add_u32_e32 v128, s1, v105
	s_sub_i32 s8, s3, s2
	v_add_u32_e32 v130, s1, v106
	v_add_u32_e32 v131, s1, v107
	v_add_u32_e32 v132, s1, v108
	s_add_i32 s1, s16, 4
	s_cmp_lt_i32 s16, s11
	s_cselect_b64 s[2:3], -1, 0
	s_and_b64 vcc, s[2:3], exec
	s_cselect_b32 s1, s1, s12
	s_cmp_lt_i32 s1, s11
	s_cselect_b32 s2, 0, s11
	s_cselect_b32 s3, s10, 0x2000
	s_sub_i32 s1, s1, s2
	s_lshl_b32 s1, s1, 6
	s_add_i32 s1, s1, s3
	s_add_i32 s2, s15, s8
	v_pk_mov_b32 v[84:85], v[2:3], v[2:3] op_sel:[0,1]
	s_add_i32 s8, s2, 0
	v_mad_i64_i32 v[2:3], s[2:3], s1, v249, v[50:51]
	s_add_i32 m0, s8, 0x10000
	v_lshl_add_u64 v[4:5], v[2:3], 0, s[18:19]
	global_load_lds_dwordx4 v[4:5], off
	v_lshl_add_u64 v[2:3], v[2:3], 0, s[20:21]
	s_add_i32 m0, s8, 0x12000
	v_pk_mov_b32 v[82:83], v[18:19], v[18:19] op_sel:[0,1]
	global_load_lds_dwordx4 v[2:3], off
	s_waitcnt vmcnt(8)
	s_waitcnt lgkmcnt(0)
	s_barrier
	s_mov_b64 s[8:9], -1
	s_cbranch_vccnz .LBB0_583
	s_mov_b32 s1, 0
	v_add_u32_e32 v6, s1, v132
	v_add_u32_e32 v7, s1, v131
	v_add_u32_e32 v8, s1, v130
	v_add_u32_e32 v9, s1, v128
	ds_read_b128 v[2:5], v6
	ds_read_b128 v[22:25], v7
	ds_read_b128 v[26:29], v8
	ds_read_b128 v[30:33], v9
	ds_read_b128 v[18:21], v6 offset:4096
	ds_read_b128 v[134:137], v7 offset:4096
	ds_read_b128 v[138:141], v8 offset:4096
	ds_read_b128 v[142:145], v9 offset:4096
	s_waitcnt lgkmcnt(7)
	v_mfma_f32_32x32x16_bf16 v[2:17], v[2:5], v[34:37], 0
	s_waitcnt lgkmcnt(6)
	v_mfma_f32_32x32x16_bf16 v[2:17], v[22:25], v[38:41], v[2:17]
	s_waitcnt lgkmcnt(5)
	v_mfma_f32_32x32x16_bf16 v[2:17], v[26:29], v[42:45], v[2:17]
	s_waitcnt lgkmcnt(4)
	v_mfma_f32_32x32x16_bf16 v[2:17], v[30:33], v[46:49], v[2:17]
	s_waitcnt lgkmcnt(3)
	v_mfma_f32_32x32x16_bf16 v[18:33], v[18:21], v[34:37], 0
	s_waitcnt lgkmcnt(2)
	v_mfma_f32_32x32x16_bf16 v[18:33], v[134:137], v[38:41], v[18:33]
	s_waitcnt lgkmcnt(1)
	v_mfma_f32_32x32x16_bf16 v[18:33], v[138:141], v[42:45], v[18:33]
	s_waitcnt lgkmcnt(0)
	v_mfma_f32_32x32x16_bf16 v[18:33], v[142:145], v[46:49], v[18:33]
	s_nop 7
	s_mov_b32 s1, 0xf149f2ca
	v_max3_f32 v66, v2, v3, v4
	v_max3_f32 v66, v66, v5, v6
	v_max3_f32 v66, v66, v7, v8
	v_max3_f32 v66, v66, v9, v10
	v_max3_f32 v66, v66, v11, v12
	v_max3_f32 v66, v66, v13, v14
	v_max3_f32 v66, v66, v15, v16
	v_max3_f32 v66, v66, v17, v18
	v_max3_f32 v66, v66, v19, v20
	v_max3_f32 v66, v66, v21, v22
	v_max3_f32 v66, v66, v23, v24
	v_max3_f32 v66, v66, v25, v26
	v_max3_f32 v66, v66, v27, v28
	v_max3_f32 v66, v66, v29, v30
	v_max3_f32 v66, v66, v31, v32
	v_max_f32_e32 v66, v66, v33
	v_cmp_lt_i32_e32 vcc, v242, v241
	v_mul_f32_e32 v66, 0x3e38aa3b, v66
	v_max_f32_e32 v66, s1, v66
	v_cndmask_b32_e32 v121, v240, v242, vcc
	v_lshlrev_b32_e32 v121, 2, v121
	ds_bpermute_b32 v121, v121, v66
	s_waitcnt lgkmcnt(0)
	v_max3_f32 v121, v110, v66, v121
	v_pk_fma_f32 v[2:3], v[2:3], s[0:1], v[120:121] op_sel:[0,0,1] op_sel_hi:[1,0,1] neg_lo:[0,0,1] neg_hi:[0,0,1]
	v_pk_fma_f32 v[18:19], v[18:19], s[0:1], v[120:121] op_sel:[0,0,1] op_sel_hi:[1,0,1] neg_lo:[0,0,1] neg_hi:[0,0,1]
	v_exp_f32_e32 v133, v2
	v_exp_f32_e32 v165, v18
	v_exp_f32_e32 v66, v3
	v_exp_f32_e32 v142, v19
	v_add_f32_e32 v143, v165, v133
	v_pk_add_f32 v[2:3], v[142:143], v[66:67]
	s_nop 0
	v_pk_add_f32 v[136:137], v[2:3], v[2:3] op_sel_hi:[0,1]
	v_pk_fma_f32 v[4:5], v[4:5], s[0:1], v[120:121] op_sel:[0,0,1] op_sel_hi:[1,0,1] neg_lo:[0,0,1] neg_hi:[0,0,1]
	v_pk_fma_f32 v[20:21], v[20:21], s[0:1], v[120:121] op_sel:[0,0,1] op_sel_hi:[1,0,1] neg_lo:[0,0,1] neg_hi:[0,0,1]
	v_exp_f32_e32 v135, v4
	v_exp_f32_e32 v143, v20
	v_exp_f32_e32 v136, v5
	v_exp_f32_e32 v144, v21
	v_add_f32_e32 v145, v143, v135
	v_pk_add_f32 v[2:3], v[144:145], v[136:137]
	s_nop 0
	v_pk_add_f32 v[138:139], v[2:3], v[2:3] op_sel_hi:[0,1]
	v_pk_fma_f32 v[6:7], v[6:7], s[0:1], v[120:121] op_sel:[0,0,1] op_sel_hi:[1,0,1] neg_lo:[0,0,1] neg_hi:[0,0,1]
	v_pk_fma_f32 v[22:23], v[22:23], s[0:1], v[120:121] op_sel:[0,0,1] op_sel_hi:[1,0,1] neg_lo:[0,0,1] neg_hi:[0,0,1]
	v_exp_f32_e32 v137, v6
	v_exp_f32_e32 v145, v22
	v_exp_f32_e32 v138, v7
	v_exp_f32_e32 v146, v23
	v_add_f32_e32 v147, v145, v137
	v_pk_add_f32 v[2:3], v[146:147], v[138:139]
	s_nop 0
	v_pk_add_f32 v[140:141], v[2:3], v[2:3] op_sel_hi:[0,1]
	v_pk_fma_f32 v[8:9], v[8:9], s[0:1], v[120:121] op_sel:[0,0,1] op_sel_hi:[1,0,1] neg_lo:[0,0,1] neg_hi:[0,0,1]
	v_pk_fma_f32 v[24:25], v[24:25], s[0:1], v[120:121] op_sel:[0,0,1] op_sel_hi:[1,0,1] neg_lo:[0,0,1] neg_hi:[0,0,1]
	v_exp_f32_e32 v139, v8
	v_exp_f32_e32 v147, v24
	v_exp_f32_e32 v140, v9
	v_exp_f32_e32 v148, v25
	v_add_f32_e32 v149, v147, v139
	v_pk_add_f32 v[2:3], v[148:149], v[140:141]
	s_nop 0
	v_pk_add_f32 v[150:151], v[2:3], v[2:3] op_sel_hi:[0,1]
	v_pk_fma_f32 v[10:11], v[10:11], s[0:1], v[120:121] op_sel:[0,0,1] op_sel_hi:[1,0,1] neg_lo:[0,0,1] neg_hi:[0,0,1]
	v_pk_fma_f32 v[26:27], v[26:27], s[0:1], v[120:121] op_sel:[0,0,1] op_sel_hi:[1,0,1] neg_lo:[0,0,1] neg_hi:[0,0,1]
; #define LAS __attribute__((address_space(3)))
; #define MFMA32(a, b, c) __builtin_amdgcn_mfma_f32_32x32x16_bf16((a), (b), (c), 0, 0, 0)
; __device__ __forceinline__ s16x4 tr_read(LAS unsigned char* p) { return __builtin_bit_cast(s16x4, __builtin_amdgcn_ds_read_tr16_b64_v4i16((LAS v4i16_t*)p)); }
; __device__ __forceinline__ unsigned cvtpk(float lo, float hi) { return pg8::cvt_pk_bf16(lo, hi); }
; template <class ScoreFn>
; __device__ __forceinline__ void attn_step(AttnState& st, const bf16x8 (&qf)[4], LAS unsigned char* kb, LAS unsigned char* vb, int lane, const ScoreFn& sf) {
;     ...
;     for (int i = 0; i < 16; ++i) { s0[i] = __builtin_amdgcn_exp2f(s0[i] - mn); s1[i] = __builtin_amdgcn_exp2f(s1[i] - mn); ps += s0[i] + s1[i]; }
;     st.l = st.l * alpha + ps; st.m = mn;
; #pragma unroll
;     for (int i = 0; i < 16; ++i) { st.o0[i] *= alpha; st.o1[i] *= alpha; }
;     __builtin_amdgcn_sched_barrier(0);
;     v4u pw[4];
;     pw[0].x = cvtpk(s0[0], s0[1]); pw[0].y = cvtpk(s0[2], s0[3]); pw[0].z = cvtpk(s0[4], s0[5]); pw[0].w = cvtpk(s0[6], s0[7]);
;     pw[1].x = cvtpk(s0[8], s0[9]); pw[1].y = cvtpk(s0[10], s0[11]); pw[1].z = cvtpk(s0[12], s0[13]); pw[1].w = cvtpk(s0[14], s0[15]);
;     pw[2].x = cvtpk(s1[0], s1[1]); pw[2].y = cvtpk(s1[2], s1[3]); pw[2].z = cvtpk(s1[4], s1[5]); pw[2].w = cvtpk(s1[6], s1[7]);
;     pw[3].x = cvtpk(s1[8], s1[9]); pw[3].y = cvtpk(s1[10], s1[11]); pw[3].z = cvtpk(s1[12], s1[13]); pw[3].w = cvtpk(s1[14], s1[15]);
;     const int i16 = lane & 15, q = i16 >> 2, p = i16 & 3, dhalf = (lane >> 4) & 1;
;     LAS unsigned char* vrow = vb + (4 * h + q) * KVP + (p & 1) * 8;
;     LAS unsigned char* vp0 = vrow + (((2 * dhalf + (p >> 1)) ^ (4 * h + q)) << 4); LAS unsigned char* vp1 = vrow + (((4 + 2 * dhalf + (p >> 1)) ^ (4 * h + q)) << 4);
; #pragma unroll
;     for (int ks = 0; ks < 4; ++ks) {
;         const s16x4 l0 = tr_read(vp0 + (16 * ks) * KVP), h0 = tr_read(vp0 + (16 * ks + 8) * KVP);
;         const s16x4 l1 = tr_read(vp1 + (16 * ks) * KVP), h1 = tr_read(vp1 + (16 * ks + 8) * KVP);
;         const bf16x8 v0 = (bf16x8){l0[0], l0[1], l0[2], l0[3], h0[0], h0[1], h0[2], h0[3]};
;         const bf16x8 v1 = (bf16x8){l1[0], l1[1], l1[2], l1[3], h1[0], h1[1], h1[2], h1[3]};
;         const bf16x8 pf = __builtin_bit_cast(bf16x8, pw[ks]);
;         st.o0 = MFMA32(v0, pf, st.o0); st.o1 = MFMA32(v1, pf, st.o1);
;     }
	v_exp_f32_e32 v141, v10
	v_exp_f32_e32 v149, v26
	v_exp_f32_e32 v150, v11
	v_exp_f32_e32 v152, v27
	v_add_f32_e32 v153, v149, v141
	v_pk_add_f32 v[2:3], v[152:153], v[150:151]
	s_nop 0
	v_pk_add_f32 v[154:155], v[2:3], v[2:3] op_sel_hi:[0,1]
	v_pk_fma_f32 v[12:13], v[12:13], s[0:1], v[120:121] op_sel:[0,0,1] op_sel_hi:[1,0,1] neg_lo:[0,0,1] neg_hi:[0,0,1]
	v_pk_fma_f32 v[28:29], v[28:29], s[0:1], v[120:121] op_sel:[0,0,1] op_sel_hi:[1,0,1] neg_lo:[0,0,1] neg_hi:[0,0,1]
	v_exp_f32_e32 v151, v12
	v_exp_f32_e32 v153, v28
	v_exp_f32_e32 v154, v13
	v_exp_f32_e32 v156, v29
	v_add_f32_e32 v157, v153, v151
	v_pk_add_f32 v[2:3], v[156:157], v[154:155]
	s_nop 0
	v_pk_add_f32 v[158:159], v[2:3], v[2:3] op_sel_hi:[0,1]
	v_pk_fma_f32 v[14:15], v[14:15], s[0:1], v[120:121] op_sel:[0,0,1] op_sel_hi:[1,0,1] neg_lo:[0,0,1] neg_hi:[0,0,1]
	v_pk_fma_f32 v[30:31], v[30:31], s[0:1], v[120:121] op_sel:[0,0,1] op_sel_hi:[1,0,1] neg_lo:[0,0,1] neg_hi:[0,0,1]
	v_exp_f32_e32 v155, v14
	v_exp_f32_e32 v157, v30
	v_exp_f32_e32 v158, v15
	v_exp_f32_e32 v160, v31
	v_add_f32_e32 v161, v157, v155
	v_pk_add_f32 v[2:3], v[160:161], v[158:159]
	s_nop 0
	v_pk_add_f32 v[162:163], v[2:3], v[2:3] op_sel_hi:[0,1]
	v_pk_fma_f32 v[16:17], v[16:17], s[0:1], v[120:121] op_sel:[0,0,1] op_sel_hi:[1,0,1] neg_lo:[0,0,1] neg_hi:[0,0,1]
	v_pk_fma_f32 v[32:33], v[32:33], s[0:1], v[120:121] op_sel:[0,0,1] op_sel_hi:[1,0,1] neg_lo:[0,0,1] neg_hi:[0,0,1]
	v_exp_f32_e32 v159, v16
	v_exp_f32_e32 v161, v32
	v_exp_f32_e32 v162, v17
	v_exp_f32_e32 v166, v33
	v_sub_f32_e32 v2, v110, v121
	v_exp_f32_e32 v18, v2
	v_add_f32_e32 v167, v161, v159
	v_pk_add_f32 v[2:3], v[166:167], v[162:163]
	v_pk_mul_f32 v[16:17], v[80:81], v[18:19] op_sel_hi:[1,0]
	v_add_f32_e32 v129, v2, v3
	v_fmac_f32_e32 v129, v109, v18
	v_pk_mul_f32 v[14:15], v[76:77], v[18:19] op_sel_hi:[1,0]
	v_pk_mul_f32 v[12:13], v[72:73], v[18:19] op_sel_hi:[1,0]
	v_pk_mul_f32 v[10:11], v[68:69], v[18:19] op_sel_hi:[1,0]
	v_pk_mul_f32 v[8:9], v[62:63], v[18:19] op_sel_hi:[1,0]
	v_pk_mul_f32 v[6:7], v[58:59], v[18:19] op_sel_hi:[1,0]
	v_pk_mul_f32 v[4:5], v[54:55], v[18:19] op_sel_hi:[1,0]
	v_pk_mul_f32 v[2:3], v[84:85], v[18:19] op_sel_hi:[1,0]
	v_pk_mul_f32 v[32:33], v[78:79], v[18:19] op_sel_hi:[1,0]
	v_pk_mul_f32 v[30:31], v[74:75], v[18:19] op_sel_hi:[1,0]
	v_pk_mul_f32 v[28:29], v[70:71], v[18:19] op_sel_hi:[1,0]
	v_pk_mul_f32 v[26:27], v[64:65], v[18:19] op_sel_hi:[1,0]
	v_pk_mul_f32 v[24:25], v[60:61], v[18:19] op_sel_hi:[1,0]
	v_pk_mul_f32 v[22:23], v[56:57], v[18:19] op_sel_hi:[1,0]
	v_pk_mul_f32 v[20:21], v[52:53], v[18:19] op_sel_hi:[1,0]
	v_pk_mul_f32 v[18:19], v[82:83], v[18:19] op_sel_hi:[1,0]
	v_cvt_pk_bf16_f32 v135, v135, v136
	v_cvt_pk_bf16_f32 v136, v137, v138
	v_cvt_pk_bf16_f32 v137, v139, v140
	v_cvt_pk_bf16_f32 v138, v141, v150
	v_cvt_pk_bf16_f32 v139, v151, v154
	v_cvt_pk_bf16_f32 v140, v155, v158
	v_cvt_pk_bf16_f32 v143, v143, v144
	v_cvt_pk_bf16_f32 v144, v145, v146
	v_cvt_pk_bf16_f32 v145, v147, v148
	v_cvt_pk_bf16_f32 v146, v149, v152
	v_cvt_pk_bf16_f32 v147, v153, v156
	v_cvt_pk_bf16_f32 v148, v157, v160
	ds_read_b64_tr_b16 v[150:151], v126
	ds_read_b64_tr_b16 v[152:153], v127
	ds_read_b64_tr_b16 v[154:155], v125
	ds_read_b64_tr_b16 v[156:157], v124
	v_cvt_pk_bf16_f32 v134, v133, v66
	v_cvt_pk_bf16_f32 v141, v159, v162
	v_cvt_pk_bf16_f32 v142, v165, v142
	s_waitcnt lgkmcnt(2)
	v_mfma_f32_32x32x16_bf16 v[2:17], v[150:153], v[134:137], v[2:17]
	v_cvt_pk_bf16_f32 v149, v161, v166
	s_mov_b64 s[8:9], 0
	s_waitcnt lgkmcnt(0)
	v_mfma_f32_32x32x16_bf16 v[18:33], v[154:157], v[134:137], v[18:33]
	ds_read_b64_tr_b16 v[134:135], v122
	ds_read_b64_tr_b16 v[136:137], v123
	ds_read_b64_tr_b16 v[150:151], v119
	ds_read_b64_tr_b16 v[152:153], v120
	s_waitcnt lgkmcnt(2)
	v_mfma_f32_32x32x16_bf16 v[2:17], v[134:137], v[138:141], v[2:17]
	s_waitcnt lgkmcnt(0)
	v_mfma_f32_32x32x16_bf16 v[18:33], v[150:153], v[138:141], v[18:33]
	ds_read_b64_tr_b16 v[134:135], v117
	ds_read_b64_tr_b16 v[136:137], v118
	ds_read_b64_tr_b16 v[138:139], v115
	ds_read_b64_tr_b16 v[140:141], v116
	s_waitcnt lgkmcnt(2)
	v_mfma_f32_32x32x16_bf16 v[2:17], v[134:137], v[142:145], v[2:17]
	s_waitcnt lgkmcnt(0)
	v_mfma_f32_32x32x16_bf16 v[18:33], v[138:141], v[142:145], v[18:33]
	ds_read_b64_tr_b16 v[134:135], v113
	ds_read_b64_tr_b16 v[136:137], v114
	ds_read_b64_tr_b16 v[138:139], v111
	ds_read_b64_tr_b16 v[140:141], v112
	s_waitcnt lgkmcnt(2)
	v_mfma_f32_32x32x16_bf16 v[2:17], v[134:137], v[146:149], v[2:17]
	s_waitcnt lgkmcnt(0)
	v_mfma_f32_32x32x16_bf16 v[18:33], v[138:141], v[146:149], v[18:33]
; #define LAS __attribute__((address_space(3)))
; #define MFMA32(a, b, c) __builtin_amdgcn_mfma_f32_32x32x16_bf16((a), (b), (c), 0, 0, 0)
; template <class ScoreFn>
; __device__ __forceinline__ void attn_step(AttnState& st, const bf16x8 (&qf)[4], LAS unsigned char* kb, LAS unsigned char* vb, int lane, const ScoreFn& sf) {
;     ...
;     LAS unsigned char* kp = kb + r * KVP; const int kx = (h ^ (r & 7)) << 4;
; #pragma unroll
;     for (int ds = 0; ds < 4; ++ds) {
;         const bf16x8 k0 = *(const LAS bf16x8*)(kp + (kx ^ (ds << 5))), k1 = *(const LAS bf16x8*)(kp + 32 * KVP + (kx ^ (ds << 5)));
;         s0 = MFMA32(k0, qf[ds], s0); s1 = MFMA32(k1, qf[ds], s1);
;     }
;     float mt = NEG_BIG;
;     __builtin_amdgcn_sched_barrier(0);
; #pragma unroll
;     for (int i = 0; i < 16; ++i) { s0[i] = sf(s0[i], (i & 3) + 8 * (i >> 2), h, r); mt = fmaxf(mt, s0[i]); if ((i & 7) == 7) __builtin_amdgcn_sched_barrier(0); }
; #pragma unroll
;     for (int i = 0; i < 16; ++i) { s1[i] = sf(s1[i], 32 + (i & 3) + 8 * (i >> 2), h, r); mt = fmaxf(mt, s1[i]); if ((i & 7) == 7) __builtin_amdgcn_sched_barrier(0); }
;     mt = fmaxf(mt, __shfl_xor(mt, 32));
.LBB0_583:
	s_andn2_b64 vcc, exec, s[8:9]
	s_cbranch_vccnz .LBB0_585
	s_mov_b32 s1, 0
	v_mov_b32_e32 v66, s14
	s_nop 5
	v_add_u32_e32 v18, s1, v132
	v_add_u32_e32 v19, s1, v131
	v_add_u32_e32 v20, s1, v130
	v_add_u32_e32 v21, s1, v128
	ds_read_b128 v[2:5], v18
	ds_read_b128 v[10:13], v19
	ds_read_b128 v[14:17], v20
	ds_read_b128 v[142:145], v21
	ds_read_b128 v[6:9], v18 offset:4096
	ds_read_b128 v[130:133], v19 offset:4096
	ds_read_b128 v[134:137], v20 offset:4096
	ds_read_b128 v[138:141], v21 offset:4096
	s_waitcnt lgkmcnt(7)
	v_mfma_f32_32x32x16_bf16 v[18:33], v[2:5], v[34:37], 0
	s_waitcnt lgkmcnt(6)
	v_mfma_f32_32x32x16_bf16 v[18:33], v[10:13], v[38:41], v[18:33]
	s_waitcnt lgkmcnt(5)
	v_mfma_f32_32x32x16_bf16 v[18:33], v[14:17], v[42:45], v[18:33]
	s_waitcnt lgkmcnt(4)
	v_mfma_f32_32x32x16_bf16 v[18:33], v[142:145], v[46:49], v[18:33]
	s_waitcnt lgkmcnt(3)
	v_mfma_f32_32x32x16_bf16 v[2:17], v[6:9], v[34:37], 0
	s_waitcnt lgkmcnt(2)
	v_mfma_f32_32x32x16_bf16 v[2:17], v[130:133], v[38:41], v[2:17]
	s_waitcnt lgkmcnt(1)
	v_mfma_f32_32x32x16_bf16 v[2:17], v[134:137], v[42:45], v[2:17]
	s_waitcnt lgkmcnt(0)
	v_mfma_f32_32x32x16_bf16 v[2:17], v[138:141], v[46:49], v[2:17]
	v_add_u32_e32 v121, v86, v66
	s_nop 6
	v_mul_f32_e32 v18, 0x3e38aa3b, v18
	v_cmp_gt_u32_e32 vcc, s17, v121
	v_add_u32_e32 v128, 1, v121
	v_mul_f32_e32 v19, 0x3e38aa3b, v19
	v_cndmask_b32_e32 v18, v250, v18, vcc
	v_cmp_gt_u32_e32 vcc, s17, v128
	v_add_u32_e32 v129, 2, v121
	v_mul_f32_e32 v20, 0x3e38aa3b, v20
	v_cndmask_b32_e32 v19, v250, v19, vcc
	v_cmp_gt_u32_e32 vcc, s17, v129
	v_add_u32_e32 v129, 3, v121
	v_mul_f32_e32 v21, 0x3e38aa3b, v21
	v_cndmask_b32_e32 v20, v250, v20, vcc
	v_cmp_gt_u32_e32 vcc, s17, v129
	v_add_u32_e32 v129, 8, v121
	v_mul_f32_e32 v22, 0x3e38aa3b, v22
	v_cndmask_b32_e32 v21, v250, v21, vcc
	v_cmp_gt_u32_e32 vcc, s17, v129
	v_add_u32_e32 v129, 9, v121
	v_mul_f32_e32 v23, 0x3e38aa3b, v23
	v_cndmask_b32_e32 v22, v250, v22, vcc
	v_cmp_gt_u32_e32 vcc, s17, v129
	v_add_u32_e32 v129, 10, v121
	v_mul_f32_e32 v24, 0x3e38aa3b, v24
	v_cndmask_b32_e32 v23, v250, v23, vcc
	v_cmp_gt_u32_e32 vcc, s17, v129
	v_add_u32_e32 v129, 11, v121
	v_mul_f32_e32 v25, 0x3e38aa3b, v25
	v_cndmask_b32_e32 v24, v250, v24, vcc
	v_cmp_gt_u32_e32 vcc, s17, v129
	v_add_u32_e32 v129, 16, v121
	v_mul_f32_e32 v26, 0x3e38aa3b, v26
	v_cndmask_b32_e32 v25, v250, v25, vcc
	v_cmp_gt_u32_e32 vcc, s17, v129
	v_add_u32_e32 v129, 17, v121
	s_mov_b32 s1, 0xf149f2ca
	v_cndmask_b32_e32 v26, v250, v26, vcc
	v_mul_f32_e32 v27, 0x3e38aa3b, v27
	v_cmp_gt_u32_e32 vcc, s17, v129
	v_add_u32_e32 v129, 18, v121
	v_max3_f32 v128, v18, s1, v19
	v_cndmask_b32_e32 v27, v250, v27, vcc
	v_mul_f32_e32 v28, 0x3e38aa3b, v28
	v_cmp_gt_u32_e32 vcc, s17, v129
	v_add_u32_e32 v129, 19, v121
	v_max3_f32 v128, v128, v20, v21
	v_cndmask_b32_e32 v28, v250, v28, vcc
	v_mul_f32_e32 v29, 0x3e38aa3b, v29
	v_cmp_gt_u32_e32 vcc, s17, v129
	v_add_u32_e32 v129, 24, v121
	v_max3_f32 v128, v128, v22, v23
	v_cndmask_b32_e32 v29, v250, v29, vcc
	v_mul_f32_e32 v30, 0x3e38aa3b, v30
	v_cmp_gt_u32_e32 vcc, s17, v129
	v_add_u32_e32 v129, 25, v121
	v_max3_f32 v128, v128, v24, v25
	v_cndmask_b32_e32 v30, v250, v30, vcc
	v_mul_f32_e32 v31, 0x3e38aa3b, v31
	v_cmp_gt_u32_e32 vcc, s17, v129
	v_add_u32_e32 v129, 26, v121
	v_max3_f32 v128, v128, v26, v27
	v_cndmask_b32_e32 v31, v250, v31, vcc
	v_mul_f32_e32 v32, 0x3e38aa3b, v32
	v_cmp_gt_u32_e32 vcc, s17, v129
	v_add_u32_e32 v121, 27, v121
	v_max3_f32 v128, v128, v28, v29
	v_cndmask_b32_e32 v32, v250, v32, vcc
	v_mul_f32_e32 v33, 0x3e38aa3b, v33
	v_cmp_gt_u32_e32 vcc, s17, v121
	v_max3_f32 v128, v128, v30, v31
	v_add_u32_e32 v66, v87, v66
	v_cndmask_b32_e32 v33, v250, v33, vcc
	v_max3_f32 v121, v128, v32, v33
	v_mul_f32_e32 v2, 0x3e38aa3b, v2
	v_cmp_gt_u32_e32 vcc, s17, v66
	v_add_u32_e32 v128, 1, v66
	v_mul_f32_e32 v3, 0x3e38aa3b, v3
	v_cndmask_b32_e32 v2, v250, v2, vcc
	v_cmp_gt_u32_e32 vcc, s17, v128
	v_add_u32_e32 v128, 2, v66
	v_mul_f32_e32 v4, 0x3e38aa3b, v4
	v_cndmask_b32_e32 v3, v250, v3, vcc
	v_cmp_gt_u32_e32 vcc, s17, v128
	v_add_u32_e32 v128, 3, v66
	v_mul_f32_e32 v5, 0x3e38aa3b, v5
	v_cndmask_b32_e32 v4, v250, v4, vcc
	v_cmp_gt_u32_e32 vcc, s17, v128
	v_add_u32_e32 v128, 8, v66
	v_mul_f32_e32 v6, 0x3e38aa3b, v6
	v_cndmask_b32_e32 v5, v250, v5, vcc
	v_cmp_gt_u32_e32 vcc, s17, v128
	v_add_u32_e32 v128, 9, v66
	v_mul_f32_e32 v7, 0x3e38aa3b, v7
	v_cndmask_b32_e32 v6, v250, v6, vcc
	v_cmp_gt_u32_e32 vcc, s17, v128
	v_add_u32_e32 v128, 10, v66
	v_mul_f32_e32 v8, 0x3e38aa3b, v8
	v_cndmask_b32_e32 v7, v250, v7, vcc
	v_cmp_gt_u32_e32 vcc, s17, v128
	v_add_u32_e32 v128, 11, v66
	v_mul_f32_e32 v9, 0x3e38aa3b, v9
	v_cndmask_b32_e32 v8, v250, v8, vcc
	v_cmp_gt_u32_e32 vcc, s17, v128
	v_add_u32_e32 v128, 16, v66
	v_mul_f32_e32 v10, 0x3e38aa3b, v10
	v_cndmask_b32_e32 v9, v250, v9, vcc
	v_cmp_gt_u32_e32 vcc, s17, v128
	v_add_u32_e32 v128, 17, v66
	v_mul_f32_e32 v11, 0x3e38aa3b, v11
	v_cndmask_b32_e32 v10, v250, v10, vcc
	v_cmp_gt_u32_e32 vcc, s17, v128
	v_add_u32_e32 v128, 18, v66
	v_max3_f32 v121, v121, v2, v3
	v_cndmask_b32_e32 v11, v250, v11, vcc
	v_mul_f32_e32 v12, 0x3e38aa3b, v12
	v_cmp_gt_u32_e32 vcc, s17, v128
	v_add_u32_e32 v128, 19, v66
	v_max3_f32 v121, v121, v4, v5
	v_cndmask_b32_e32 v12, v250, v12, vcc
	v_mul_f32_e32 v13, 0x3e38aa3b, v13
	v_cmp_gt_u32_e32 vcc, s17, v128
	v_add_u32_e32 v128, 24, v66
	v_max3_f32 v121, v121, v6, v7
	v_cndmask_b32_e32 v13, v250, v13, vcc
	v_mul_f32_e32 v14, 0x3e38aa3b, v14
	v_cmp_gt_u32_e32 vcc, s17, v128
	v_add_u32_e32 v128, 25, v66
	v_max3_f32 v121, v121, v8, v9
	v_cndmask_b32_e32 v14, v250, v14, vcc
	v_mul_f32_e32 v15, 0x3e38aa3b, v15
	v_cmp_gt_u32_e32 vcc, s17, v128
	v_add_u32_e32 v128, 26, v66
	v_max3_f32 v121, v121, v10, v11
	v_cndmask_b32_e32 v15, v250, v15, vcc
	v_mul_f32_e32 v16, 0x3e38aa3b, v16
	v_cmp_gt_u32_e32 vcc, s17, v128
	v_add_u32_e32 v66, 27, v66
	v_max3_f32 v121, v121, v12, v13
	v_cndmask_b32_e32 v16, v250, v16, vcc
	v_mul_f32_e32 v17, 0x3e38aa3b, v17
	v_cmp_gt_u32_e32 vcc, s17, v66
	v_max3_f32 v121, v121, v14, v15
	s_nop 0
	v_cndmask_b32_e32 v17, v250, v17, vcc
	v_cmp_lt_i32_e32 vcc, v242, v241
	v_max3_f32 v66, v121, v16, v17
	s_nop 0
	v_cndmask_b32_e32 v121, v240, v242, vcc
	v_lshlrev_b32_e32 v121, 2, v121
	ds_bpermute_b32 v121, v121, v66
	s_waitcnt lgkmcnt(0)
; #define LAS __attribute__((address_space(3)))
; #define MFMA32(a, b, c) __builtin_amdgcn_mfma_f32_32x32x16_bf16((a), (b), (c), 0, 0, 0)
; __device__ __forceinline__ unsigned cvtpk(float lo, float hi) { return pg8::cvt_pk_bf16(lo, hi); }
; template <class ScoreFn>
; __device__ __forceinline__ void attn_step(AttnState& st, const bf16x8 (&qf)[4], LAS unsigned char* kb, LAS unsigned char* vb, int lane, const ScoreFn& sf) {
;     ...
;     mt = fmaxf(mt, __shfl_xor(mt, 32));
;     const float mn = fmaxf(st.m, mt), alpha = __builtin_amdgcn_exp2f(st.m - mn);
;     float ps = 0.f;
; #pragma unroll
;     for (int i = 0; i < 16; ++i) { s0[i] = __builtin_amdgcn_exp2f(s0[i] - mn); s1[i] = __builtin_amdgcn_exp2f(s1[i] - mn); ps += s0[i] + s1[i]; }
;     st.l = st.l * alpha + ps; st.m = mn;
; #pragma unroll
;     for (int i = 0; i < 16; ++i) { st.o0[i] *= alpha; st.o1[i] *= alpha; }
;     __builtin_amdgcn_sched_barrier(0);
;     v4u pw[4];
;     pw[0].x = cvtpk(s0[0], s0[1]); pw[0].y = cvtpk(s0[2], s0[3]); pw[0].z = cvtpk(s0[4], s0[5]); pw[0].w = cvtpk(s0[6], s0[7]);
;     pw[1].x = cvtpk(s0[8], s0[9]); pw[1].y = cvtpk(s0[10], s0[11]); pw[1].z = cvtpk(s0[12], s0[13]); pw[1].w = cvtpk(s0[14], s0[15]);
;     pw[2].x = cvtpk(s1[0], s1[1]); pw[2].y = cvtpk(s1[2], s1[3]); pw[2].z = cvtpk(s1[4], s1[5]); pw[2].w = cvtpk(s1[6], s1[7]);
;     pw[3].x = cvtpk(s1[8], s1[9]); pw[3].y = cvtpk(s1[10], s1[11]); pw[3].z = cvtpk(s1[12], s1[13]); pw[3].w = cvtpk(s1[14], s1[15]);
;     const int i16 = lane & 15, q = i16 >> 2, p = i16 & 3, dhalf = (lane >> 4) & 1;
;     LAS unsigned char* vrow = vb + (4 * h + q) * KVP + (p & 1) * 8;
;     LAS unsigned char* vp0 = vrow + (((2 * dhalf + (p >> 1)) ^ (4 * h + q)) << 4); LAS unsigned char* vp1 = vrow + (((4 + 2 * dhalf + (p >> 1)) ^ (4 * h + q)) << 4);
; #pragma unroll
;     for (int ks = 0; ks < 4; ++ks) {
;         const s16x4 l0 = tr_read(vp0 + (16 * ks) * KVP), h0 = tr_read(vp0 + (16 * ks + 8) * KVP);
;         const s16x4 l1 = tr_read(vp1 + (16 * ks) * KVP), h1 = tr_read(vp1 + (16 * ks + 8) * KVP);
;         const bf16x8 v0 = (bf16x8){l0[0], l0[1], l0[2], l0[3], h0[0], h0[1], h0[2], h0[3]};
;         const bf16x8 v1 = (bf16x8){l1[0], l1[1], l1[2], l1[3], h1[0], h1[1], h1[2], h1[3]};
;         const bf16x8 pf = __builtin_bit_cast(bf16x8, pw[ks]);
;         st.o0 = MFMA32(v0, pf, st.o0); st.o1 = MFMA32(v1, pf, st.o1);
;     }
	v_max3_f32 v121, v110, v66, v121
	v_sub_f32_e32 v2, v2, v121
	v_sub_f32_e32 v18, v18, v121
	v_exp_f32_e32 v159, v2
	v_sub_f32_e32 v2, v19, v121
	v_exp_f32_e32 v158, v18
	v_exp_f32_e32 v66, v2
	v_sub_f32_e32 v2, v3, v121
	v_exp_f32_e32 v128, v2
	v_add_f32_e32 v129, v159, v158
	v_pk_add_f32 v[2:3], v[128:129], v[66:67]
	s_nop 0
	v_pk_add_f32 v[130:131], v[2:3], v[2:3] op_sel_hi:[0,1]
	v_sub_f32_e32 v2, v20, v121
	v_exp_f32_e32 v160, v2
	v_sub_f32_e32 v2, v4, v121
	v_exp_f32_e32 v161, v2
	v_sub_f32_e32 v2, v21, v121
	v_exp_f32_e32 v130, v2
	v_sub_f32_e32 v2, v5, v121
	v_exp_f32_e32 v132, v2
	v_add_f32_e32 v133, v161, v160
	v_pk_add_f32 v[2:3], v[132:133], v[130:131]
	s_nop 0
	v_pk_add_f32 v[134:135], v[2:3], v[2:3] op_sel_hi:[0,1]
	v_sub_f32_e32 v2, v22, v121
	v_exp_f32_e32 v131, v2
	v_sub_f32_e32 v2, v6, v121
	v_exp_f32_e32 v133, v2
	v_sub_f32_e32 v2, v23, v121
	v_exp_f32_e32 v134, v2
	v_sub_f32_e32 v2, v7, v121
	v_exp_f32_e32 v136, v2
	v_add_f32_e32 v137, v133, v131
	v_pk_add_f32 v[2:3], v[136:137], v[134:135]
	s_nop 0
	v_pk_add_f32 v[138:139], v[2:3], v[2:3] op_sel_hi:[0,1]
	v_sub_f32_e32 v2, v24, v121
	v_exp_f32_e32 v135, v2
	v_sub_f32_e32 v2, v8, v121
	v_exp_f32_e32 v137, v2
	v_sub_f32_e32 v2, v25, v121
	v_exp_f32_e32 v138, v2
	v_sub_f32_e32 v2, v9, v121
	v_exp_f32_e32 v140, v2
	v_add_f32_e32 v141, v137, v135
	v_pk_add_f32 v[2:3], v[140:141], v[138:139]
	s_nop 0
	v_pk_add_f32 v[142:143], v[2:3], v[2:3] op_sel_hi:[0,1]
	v_sub_f32_e32 v2, v26, v121
	v_exp_f32_e32 v139, v2
	v_sub_f32_e32 v2, v10, v121
	v_exp_f32_e32 v141, v2
	v_sub_f32_e32 v2, v27, v121
	v_exp_f32_e32 v142, v2
	v_sub_f32_e32 v2, v11, v121
	v_exp_f32_e32 v144, v2
	v_add_f32_e32 v145, v141, v139
	v_pk_add_f32 v[2:3], v[144:145], v[142:143]
	s_nop 0
	v_pk_add_f32 v[146:147], v[2:3], v[2:3] op_sel_hi:[0,1]
	v_sub_f32_e32 v2, v28, v121
	v_exp_f32_e32 v143, v2
	v_sub_f32_e32 v2, v12, v121
	v_exp_f32_e32 v145, v2
	v_sub_f32_e32 v2, v29, v121
	v_exp_f32_e32 v146, v2
	v_sub_f32_e32 v2, v13, v121
	v_exp_f32_e32 v148, v2
	v_add_f32_e32 v149, v145, v143
	v_pk_add_f32 v[2:3], v[148:149], v[146:147]
	s_nop 0
	v_pk_add_f32 v[150:151], v[2:3], v[2:3] op_sel_hi:[0,1]
	v_sub_f32_e32 v2, v30, v121
	v_exp_f32_e32 v147, v2
	v_sub_f32_e32 v2, v14, v121
	v_exp_f32_e32 v149, v2
	v_sub_f32_e32 v2, v31, v121
	v_exp_f32_e32 v150, v2
	v_sub_f32_e32 v2, v15, v121
	v_exp_f32_e32 v152, v2
	v_add_f32_e32 v153, v149, v147
	v_pk_add_f32 v[2:3], v[152:153], v[150:151]
	s_nop 0
	v_pk_add_f32 v[154:155], v[2:3], v[2:3] op_sel_hi:[0,1]
	v_sub_f32_e32 v2, v32, v121
	v_exp_f32_e32 v151, v2
	v_sub_f32_e32 v2, v16, v121
	v_exp_f32_e32 v153, v2
	v_sub_f32_e32 v2, v33, v121
	v_exp_f32_e32 v154, v2
	v_sub_f32_e32 v2, v17, v121
	v_exp_f32_e32 v156, v2
	v_sub_f32_e32 v2, v110, v121
	v_exp_f32_e32 v18, v2
	v_add_f32_e32 v157, v153, v151
	v_pk_add_f32 v[2:3], v[156:157], v[154:155]
	v_pk_mul_f32 v[16:17], v[80:81], v[18:19] op_sel_hi:[1,0]
	v_add_f32_e32 v129, v2, v3
	v_fmac_f32_e32 v129, v109, v18
	v_pk_mul_f32 v[14:15], v[76:77], v[18:19] op_sel_hi:[1,0]
	v_pk_mul_f32 v[12:13], v[72:73], v[18:19] op_sel_hi:[1,0]
	v_pk_mul_f32 v[10:11], v[68:69], v[18:19] op_sel_hi:[1,0]
	v_pk_mul_f32 v[8:9], v[62:63], v[18:19] op_sel_hi:[1,0]
	v_pk_mul_f32 v[6:7], v[58:59], v[18:19] op_sel_hi:[1,0]
	v_pk_mul_f32 v[4:5], v[54:55], v[18:19] op_sel_hi:[1,0]
	v_pk_mul_f32 v[2:3], v[84:85], v[18:19] op_sel_hi:[1,0]
	v_pk_mul_f32 v[32:33], v[78:79], v[18:19] op_sel_hi:[1,0]
	v_pk_mul_f32 v[30:31], v[74:75], v[18:19] op_sel_hi:[1,0]
	v_pk_mul_f32 v[28:29], v[70:71], v[18:19] op_sel_hi:[1,0]
	v_pk_mul_f32 v[26:27], v[64:65], v[18:19] op_sel_hi:[1,0]
	v_pk_mul_f32 v[24:25], v[60:61], v[18:19] op_sel_hi:[1,0]
	v_pk_mul_f32 v[22:23], v[56:57], v[18:19] op_sel_hi:[1,0]
	v_pk_mul_f32 v[20:21], v[52:53], v[18:19] op_sel_hi:[1,0]
	v_pk_mul_f32 v[18:19], v[82:83], v[18:19] op_sel_hi:[1,0]
	ds_read_b64_tr_b16 v[72:73], v126
	ds_read_b64_tr_b16 v[74:75], v127
	ds_read_b64_tr_b16 v[76:77], v125
	ds_read_b64_tr_b16 v[78:79], v124
	v_cvt_pk_bf16_f32 v52, v158, v66
	v_cvt_pk_bf16_f32 v53, v160, v130
	v_cvt_pk_bf16_f32 v54, v131, v134
	v_cvt_pk_bf16_f32 v55, v135, v138
	v_cvt_pk_bf16_f32 v56, v139, v142
	v_cvt_pk_bf16_f32 v57, v143, v146
	s_waitcnt lgkmcnt(2)
	v_mfma_f32_32x32x16_bf16 v[2:17], v[72:75], v[52:55], v[2:17]
	v_cvt_pk_bf16_f32 v58, v147, v150
	v_cvt_pk_bf16_f32 v59, v151, v154
	v_cvt_pk_bf16_f32 v60, v159, v128
	v_cvt_pk_bf16_f32 v61, v161, v132
	v_cvt_pk_bf16_f32 v62, v133, v136
	v_cvt_pk_bf16_f32 v63, v137, v140
	v_cvt_pk_bf16_f32 v68, v141, v144
	s_waitcnt lgkmcnt(0)
	v_mfma_f32_32x32x16_bf16 v[18:33], v[76:79], v[52:55], v[18:33]
	ds_read_b64_tr_b16 v[52:53], v122
	ds_read_b64_tr_b16 v[54:55], v123
	ds_read_b64_tr_b16 v[72:73], v119
	ds_read_b64_tr_b16 v[74:75], v120
	v_cvt_pk_bf16_f32 v69, v145, v148
	v_cvt_pk_bf16_f32 v70, v149, v152
	v_cvt_pk_bf16_f32 v71, v153, v156
	s_waitcnt lgkmcnt(2)
	v_mfma_f32_32x32x16_bf16 v[2:17], v[52:55], v[56:59], v[2:17]
	s_waitcnt lgkmcnt(0)
	v_mfma_f32_32x32x16_bf16 v[18:33], v[72:75], v[56:59], v[18:33]
	ds_read_b64_tr_b16 v[52:53], v117
	ds_read_b64_tr_b16 v[54:55], v118
	ds_read_b64_tr_b16 v[56:57], v115
	ds_read_b64_tr_b16 v[58:59], v116
	s_waitcnt lgkmcnt(2)
	v_mfma_f32_32x32x16_bf16 v[2:17], v[52:55], v[60:63], v[2:17]
	s_waitcnt lgkmcnt(0)
	v_mfma_f32_32x32x16_bf16 v[18:33], v[56:59], v[60:63], v[18:33]
	ds_read_b64_tr_b16 v[52:53], v113
	ds_read_b64_tr_b16 v[54:55], v114
	ds_read_b64_tr_b16 v[56:57], v111
	ds_read_b64_tr_b16 v[58:59], v112
	s_waitcnt lgkmcnt(2)
	v_mfma_f32_32x32x16_bf16 v[2:17], v[52:55], v[68:71], v[2:17]
	s_waitcnt lgkmcnt(0)
	v_mfma_f32_32x32x16_bf16 v[18:33], v[56:59], v[68:71], v[18:33]

; #define LAS __attribute__((address_space(3)))
; #define MFMA32(a, b, c) __builtin_amdgcn_mfma_f32_32x32x16_bf16((a), (b), (c), 0, 0, 0)
; #define WG_BAR() do { asm volatile("s_waitcnt lgkmcnt(0)" ::: "memory"); __builtin_amdgcn_s_barrier(); asm volatile("" ::: "memory"); } while (0)
; #define ATT_DMA(t) do { const int t_ = (t) < NS ? (t) : NS - 1; const size_t ro_ = (size_t)TILE_ROW(t_) * ZC; LAS unsigned char* d_ = dk0 + ((t) % ATT_NB) * KV_BUF; \
;         __builtin_amdgcn_global_load_lds((const unsigned*)(gk + ro_), (LAS unsigned*)d_, 16, 0, 0); __builtin_amdgcn_global_load_lds((const unsigned*)(gv + ro_), (LAS unsigned*)(d_ + KV_TILE), 16, 0, 0); } while (0)
; template <class ScoreFn>
; __device__ __forceinline__ void attn_step(AttnState& st, const bf16x8 (&qf)[4], LAS unsigned char* kb, LAS unsigned char* vb, int lane, const ScoreFn& sf) {
;     ...
;     LAS unsigned char* kp = kb + r * KVP; const int kx = (h ^ (r & 7)) << 4;
; #pragma unroll
;     for (int ds = 0; ds < 4; ++ds) {
;         const bf16x8 k0 = *(const LAS bf16x8*)(kp + (kx ^ (ds << 5))), k1 = *(const LAS bf16x8*)(kp + 32 * KVP + (kx ^ (ds << 5)));
;         s0 = MFMA32(k0, qf[ds], s0); s1 = MFMA32(k1, qf[ds], s1);
;     }
;     float mt = NEG_BIG;
;     __builtin_amdgcn_sched_barrier(0);
; #pragma unroll
;     for (int i = 0; i < 16; ++i) { s0[i] = sf(s0[i], (i & 3) + 8 * (i >> 2), h, r); mt = fmaxf(mt, s0[i]); if ((i & 7) == 7) __builtin_amdgcn_sched_barrier(0); }
; #pragma unroll
;     for (int i = 0; i < 16; ++i) { s1[i] = sf(s1[i], 32 + (i & 3) + 8 * (i >> 2), h, r); mt = fmaxf(mt, s1[i]); if ((i & 7) == 7) __builtin_amdgcn_sched_barrier(0); }
;     mt = fmaxf(mt, __shfl_xor(mt, 32));
; template <bool ISB>
; __device__ __forceinline__ void attn_wg_item(Frame& F, int l, int idx) {
;     ...
;     AttnState st;
; #pragma unroll
;     for (int i = 0; i < 16; ++i) { st.o0[i] = 0.f; st.o1[i] = 0.f; }
;     st.m = NEG_BIG; st.l = 0.f;
; #pragma unroll
;     for (int t = 0; t < ATT_D; ++t) ATT_DMA(t);
;     if (ISB && lat) {
;         const float* bsrc = KIN(I_NBBIAS) + (size_t)(l * 8 + (ix & 7)) * 465;
;         if (tid < 465) tab[64 + tid] = bsrc[tid] * LOG2E; }
;     for (int s = 0; s < NS; ++s) {
;         ATT_DMA(s + ATT_D);
;         asm volatile("s_waitcnt vmcnt(8)" ::: "memory");
;         WG_BAR();
;         LAS unsigned char* cur = ring + (s % ATT_NB) * KV_BUF;
.LBB0_618:
	s_mul_hi_u32 s1, s80, 0xaaaaaaab
	s_lshr_b32 s1, s1, 2
	s_mul_i32 s1, s1, 0x18000
	v_readlane_b32 s2, v253, 14
	s_sub_i32 s74, s2, s1
	v_readlane_b32 s2, v253, 16
	s_sub_i32 s1, s2, s1
	s_mul_hi_u32 s2, s82, 0xaaaaaaab
	s_lshr_b32 s2, s2, 2
	s_add_i32 s75, s82, 4
	s_mul_i32 s2, s2, 0x18000
	s_sub_i32 s2, s81, s2
	s_cmp_lt_i32 s82, s78
	v_add_u32_e32 v139, s2, v96
	v_add_u32_e32 v138, s2, v97
	v_add_u32_e32 v137, s2, v98
	v_add_u32_e32 v136, s2, v99
	v_add3_u32 v134, s2, v100, v101
	v_add3_u32 v133, s2, v102, v101
	v_add3_u32 v129, s2, v103, v101
	v_add3_u32 v128, s2, v104, v101
	v_add3_u32 v125, s2, v105, v101
	v_add3_u32 v124, s2, v106, v101
	v_add3_u32 v121, s2, v107, v101
	v_add3_u32 v120, s2, v108, v101
	v_add3_u32 v118, s2, v110, v101
	v_add3_u32 v119, s2, v111, v101
	v_add3_u32 v122, s2, v112, v101
	v_add3_u32 v123, s2, v113, v101
	v_add3_u32 v126, s2, v114, v101
	v_add3_u32 v127, s2, v115, v101
	v_add3_u32 v132, s2, v116, v101
	v_add3_u32 v135, s2, v117, v101
	s_cselect_b64 s[2:3], -1, 0
	s_and_b64 vcc, s[2:3], exec
	s_cselect_b32 s2, s75, s79
	s_cmp_lt_i32 s2, s78
	s_cselect_b32 s3, 0, s78
	s_cselect_b32 s75, s77, 0x2000
	s_sub_i32 s2, s2, s3
	s_lshl_b32 s2, s2, 6
	s_add_i32 s2, s2, s75
	s_add_i32 s3, s81, s74
	s_add_i32 m0, s3, 0
	v_mad_i64_i32 v[34:35], s[2:3], s2, v249, v[92:93]
	v_lshl_add_u64 v[36:37], v[34:35], 0, s[86:87]
	s_add_i32 s1, s81, s1
	global_load_lds_dwordx4 v[36:37], off
	v_lshl_add_u64 v[34:35], v[34:35], 0, s[96:97]
	s_add_i32 m0, s1, 0
	s_mov_b64 s[74:75], -1
	global_load_lds_dwordx4 v[34:35], off
	s_waitcnt vmcnt(8)
	s_waitcnt lgkmcnt(0)
	s_barrier
	s_cbranch_vccnz .LBB0_620
	s_mov_b32 s1, 0
	v_add_u32_e32 v38, s1, v139
	v_add_u32_e32 v39, s1, v138
	v_add_u32_e32 v40, s1, v137
	v_add_u32_e32 v41, s1, v136
	ds_read_b128 v[34:37], v38
	ds_read_b128 v[54:57], v39
	ds_read_b128 v[58:61], v40
	ds_read_b128 v[62:65], v41
	ds_read_b128 v[50:53], v38 offset:4096
	ds_read_b128 v[84:87], v39 offset:4096
	ds_read_b128 v[88:91], v40 offset:4096
	ds_read_b128 v[140:143], v41 offset:4096
	s_waitcnt lgkmcnt(7)
	v_mfma_f32_32x32x16_bf16 v[34:49], v[34:37], v[68:71], 0
	s_waitcnt lgkmcnt(6)
	v_mfma_f32_32x32x16_bf16 v[34:49], v[54:57], v[72:75], v[34:49]
	s_waitcnt lgkmcnt(5)
	v_mfma_f32_32x32x16_bf16 v[34:49], v[58:61], v[76:79], v[34:49]
	s_waitcnt lgkmcnt(4)
	v_mfma_f32_32x32x16_bf16 v[34:49], v[62:65], v[80:83], v[34:49]
	s_waitcnt lgkmcnt(3)
	v_mfma_f32_32x32x16_bf16 v[50:65], v[50:53], v[68:71], 0
	s_waitcnt lgkmcnt(2)
	v_mfma_f32_32x32x16_bf16 v[50:65], v[84:87], v[72:75], v[50:65]
	s_waitcnt lgkmcnt(1)
	v_mfma_f32_32x32x16_bf16 v[50:65], v[88:91], v[76:79], v[50:65]
	s_waitcnt lgkmcnt(0)
	v_mfma_f32_32x32x16_bf16 v[50:65], v[140:143], v[80:83], v[50:65]
	s_nop 7
	s_mov_b32 s1, 0xf149f2ca
	v_max3_f32 v66, v34, v35, v36
	v_max3_f32 v66, v66, v37, v38
	v_max3_f32 v66, v66, v39, v40
	v_max3_f32 v66, v66, v41, v42
	v_max3_f32 v66, v66, v43, v44
	v_max3_f32 v66, v66, v45, v46
	v_max3_f32 v66, v66, v47, v48
	v_max3_f32 v66, v66, v49, v50
	v_max3_f32 v66, v66, v51, v52
	v_max3_f32 v66, v66, v53, v54
	v_max3_f32 v66, v66, v55, v56
	v_max3_f32 v66, v66, v57, v58
	v_max3_f32 v66, v66, v59, v60
	v_max3_f32 v66, v66, v61, v62
	v_max3_f32 v66, v66, v63, v64
	v_max_f32_e32 v66, v66, v65
	v_cmp_lt_i32_e32 vcc, v242, v241
	v_mul_f32_e32 v66, 0x3e38aa3b, v66
	v_max_f32_e32 v66, s1, v66
	v_cndmask_b32_e32 v84, v240, v242, vcc
	v_lshlrev_b32_e32 v84, 2, v84
	ds_bpermute_b32 v84, v84, v66
	s_waitcnt lgkmcnt(0)
; #define LAS __attribute__((address_space(3)))
; #define MFMA32(a, b, c) __builtin_amdgcn_mfma_f32_32x32x16_bf16((a), (b), (c), 0, 0, 0)
; __device__ __forceinline__ unsigned cvtpk(float lo, float hi) { return pg8::cvt_pk_bf16(lo, hi); }
; template <class ScoreFn>
; __device__ __forceinline__ void attn_step(AttnState& st, const bf16x8 (&qf)[4], LAS unsigned char* kb, LAS unsigned char* vb, int lane, const ScoreFn& sf) {
;     ...
;     mt = fmaxf(mt, __shfl_xor(mt, 32));
;     const float mn = fmaxf(st.m, mt), alpha = __builtin_amdgcn_exp2f(st.m - mn);
;     float ps = 0.f;
; #pragma unroll
;     for (int i = 0; i < 16; ++i) { s0[i] = __builtin_amdgcn_exp2f(s0[i] - mn); s1[i] = __builtin_amdgcn_exp2f(s1[i] - mn); ps += s0[i] + s1[i]; }
;     st.l = st.l * alpha + ps; st.m = mn;
; #pragma unroll
;     for (int i = 0; i < 16; ++i) { st.o0[i] *= alpha; st.o1[i] *= alpha; }
;     __builtin_amdgcn_sched_barrier(0);
;     v4u pw[4];
;     pw[0].x = cvtpk(s0[0], s0[1]); pw[0].y = cvtpk(s0[2], s0[3]); pw[0].z = cvtpk(s0[4], s0[5]); pw[0].w = cvtpk(s0[6], s0[7]);
;     pw[1].x = cvtpk(s0[8], s0[9]); pw[1].y = cvtpk(s0[10], s0[11]); pw[1].z = cvtpk(s0[12], s0[13]); pw[1].w = cvtpk(s0[14], s0[15]);
;     pw[2].x = cvtpk(s1[0], s1[1]); pw[2].y = cvtpk(s1[2], s1[3]); pw[2].z = cvtpk(s1[4], s1[5]); pw[2].w = cvtpk(s1[6], s1[7]);
;     pw[3].x = cvtpk(s1[8], s1[9]); pw[3].y = cvtpk(s1[10], s1[11]); pw[3].z = cvtpk(s1[12], s1[13]); pw[3].w = cvtpk(s1[14], s1[15]);
;     const int i16 = lane & 15, q = i16 >> 2, p = i16 & 3, dhalf = (lane >> 4) & 1;
;     LAS unsigned char* vrow = vb + (4 * h + q) * KVP + (p & 1) * 8;
;     LAS unsigned char* vp0 = vrow + (((2 * dhalf + (p >> 1)) ^ (4 * h + q)) << 4); LAS unsigned char* vp1 = vrow + (((4 + 2 * dhalf + (p >> 1)) ^ (4 * h + q)) << 4);
; #pragma unroll
;     for (int ks = 0; ks < 4; ++ks) {
;         const s16x4 l0 = tr_read(vp0 + (16 * ks) * KVP), h0 = tr_read(vp0 + (16 * ks + 8) * KVP);
;         const s16x4 l1 = tr_read(vp1 + (16 * ks) * KVP), h1 = tr_read(vp1 + (16 * ks + 8) * KVP);
;         const bf16x8 v0 = (bf16x8){l0[0], l0[1], l0[2], l0[3], h0[0], h0[1], h0[2], h0[3]};
;         const bf16x8 v1 = (bf16x8){l1[0], l1[1], l1[2], l1[3], h1[0], h1[1], h1[2], h1[3]};
;         const bf16x8 pf = __builtin_bit_cast(bf16x8, pw[ks]);
;         st.o0 = MFMA32(v0, pf, st.o0); st.o1 = MFMA32(v1, pf, st.o1);
;     }
	v_max3_f32 v140, v131, v66, v84
	v_pk_fma_f32 v[34:35], v[34:35], s[0:1], v[140:141] op_sel_hi:[1,0,0] neg_lo:[0,0,1] neg_hi:[0,0,1]
	v_pk_fma_f32 v[50:51], v[50:51], s[0:1], v[140:141] op_sel_hi:[1,0,0] neg_lo:[0,0,1] neg_hi:[0,0,1]
	v_exp_f32_e32 v142, v34
	v_exp_f32_e32 v165, v50
	v_exp_f32_e32 v66, v35
	v_exp_f32_e32 v84, v51
	v_add_f32_e32 v85, v165, v142
	v_pk_add_f32 v[34:35], v[84:85], v[66:67]
	s_nop 0
	v_pk_add_f32 v[86:87], v[34:35], v[34:35] op_sel_hi:[0,1]
	v_pk_fma_f32 v[36:37], v[36:37], s[0:1], v[140:141] op_sel_hi:[1,0,0] neg_lo:[0,0,1] neg_hi:[0,0,1]
	v_pk_fma_f32 v[52:53], v[52:53], s[0:1], v[140:141] op_sel_hi:[1,0,0] neg_lo:[0,0,1] neg_hi:[0,0,1]
	v_exp_f32_e32 v85, v36
	v_exp_f32_e32 v170, v52
	v_exp_f32_e32 v86, v37
	v_exp_f32_e32 v90, v53
	v_add_f32_e32 v91, v170, v85
	v_pk_add_f32 v[34:35], v[90:91], v[86:87]
	s_nop 0
	v_pk_add_f32 v[88:89], v[34:35], v[34:35] op_sel_hi:[0,1]
	v_pk_fma_f32 v[38:39], v[38:39], s[0:1], v[140:141] op_sel_hi:[1,0,0] neg_lo:[0,0,1] neg_hi:[0,0,1]
	v_pk_fma_f32 v[54:55], v[54:55], s[0:1], v[140:141] op_sel_hi:[1,0,0] neg_lo:[0,0,1] neg_hi:[0,0,1]
	v_exp_f32_e32 v87, v38
	v_exp_f32_e32 v91, v54
	v_exp_f32_e32 v88, v39
	v_exp_f32_e32 v150, v55
	v_add_f32_e32 v151, v91, v87
	v_pk_add_f32 v[34:35], v[150:151], v[88:89]
	s_nop 0
	v_pk_add_f32 v[146:147], v[34:35], v[34:35] op_sel_hi:[0,1]
	v_pk_fma_f32 v[40:41], v[40:41], s[0:1], v[140:141] op_sel_hi:[1,0,0] neg_lo:[0,0,1] neg_hi:[0,0,1]
	v_pk_fma_f32 v[56:57], v[56:57], s[0:1], v[140:141] op_sel_hi:[1,0,0] neg_lo:[0,0,1] neg_hi:[0,0,1]
	v_exp_f32_e32 v89, v40
	v_exp_f32_e32 v151, v56
	v_exp_f32_e32 v146, v41
	v_exp_f32_e32 v152, v57
	v_add_f32_e32 v153, v151, v89
	v_pk_add_f32 v[34:35], v[152:153], v[146:147]
	s_nop 0
	v_pk_add_f32 v[148:149], v[34:35], v[34:35] op_sel_hi:[0,1]
	v_pk_fma_f32 v[42:43], v[42:43], s[0:1], v[140:141] op_sel_hi:[1,0,0] neg_lo:[0,0,1] neg_hi:[0,0,1]
	v_pk_fma_f32 v[58:59], v[58:59], s[0:1], v[140:141] op_sel_hi:[1,0,0] neg_lo:[0,0,1] neg_hi:[0,0,1]
	v_exp_f32_e32 v147, v42
	v_exp_f32_e32 v153, v58
	v_exp_f32_e32 v148, v43
	v_exp_f32_e32 v154, v59
	v_add_f32_e32 v155, v153, v147
	v_pk_add_f32 v[34:35], v[154:155], v[148:149]
	s_nop 0
	v_pk_add_f32 v[156:157], v[34:35], v[34:35] op_sel_hi:[0,1]
	v_pk_fma_f32 v[44:45], v[44:45], s[0:1], v[140:141] op_sel_hi:[1,0,0] neg_lo:[0,0,1] neg_hi:[0,0,1]
	v_pk_fma_f32 v[60:61], v[60:61], s[0:1], v[140:141] op_sel_hi:[1,0,0] neg_lo:[0,0,1] neg_hi:[0,0,1]
	v_exp_f32_e32 v149, v44
	v_exp_f32_e32 v155, v60
	v_exp_f32_e32 v156, v45
	v_exp_f32_e32 v158, v61
	v_add_f32_e32 v159, v155, v149
	v_pk_add_f32 v[34:35], v[158:159], v[156:157]
	s_nop 0
	v_pk_add_f32 v[160:161], v[34:35], v[34:35] op_sel_hi:[0,1]
	v_pk_fma_f32 v[46:47], v[46:47], s[0:1], v[140:141] op_sel_hi:[1,0,0] neg_lo:[0,0,1] neg_hi:[0,0,1]
	v_pk_fma_f32 v[62:63], v[62:63], s[0:1], v[140:141] op_sel_hi:[1,0,0] neg_lo:[0,0,1] neg_hi:[0,0,1]
	v_exp_f32_e32 v157, v46
	v_exp_f32_e32 v159, v62
	v_exp_f32_e32 v160, v47
	v_exp_f32_e32 v162, v63
	v_add_f32_e32 v163, v159, v157
	v_pk_add_f32 v[34:35], v[162:163], v[160:161]
	s_nop 0
	v_pk_add_f32 v[166:167], v[34:35], v[34:35] op_sel_hi:[0,1]
	v_pk_fma_f32 v[48:49], v[48:49], s[0:1], v[140:141] op_sel_hi:[1,0,0] neg_lo:[0,0,1] neg_hi:[0,0,1]
	v_pk_fma_f32 v[64:65], v[64:65], s[0:1], v[140:141] op_sel_hi:[1,0,0] neg_lo:[0,0,1] neg_hi:[0,0,1]
	v_exp_f32_e32 v161, v48
	v_exp_f32_e32 v163, v64
	v_exp_f32_e32 v166, v49
	v_exp_f32_e32 v168, v65
	v_sub_f32_e32 v34, v131, v140
	v_exp_f32_e32 v50, v34
	v_add_f32_e32 v169, v163, v161
	v_pk_add_f32 v[34:35], v[168:169], v[166:167]
	v_pk_mul_f32 v[48:49], v[32:33], v[50:51] op_sel_hi:[1,0]
	v_add_f32_e32 v141, v34, v35
	v_fmac_f32_e32 v141, v130, v50
	v_pk_mul_f32 v[46:47], v[30:31], v[50:51] op_sel_hi:[1,0]
	v_pk_mul_f32 v[44:45], v[28:29], v[50:51] op_sel_hi:[1,0]
	v_pk_mul_f32 v[42:43], v[26:27], v[50:51] op_sel_hi:[1,0]
	v_pk_mul_f32 v[40:41], v[24:25], v[50:51] op_sel_hi:[1,0]
	v_pk_mul_f32 v[38:39], v[22:23], v[50:51] op_sel_hi:[1,0]
	v_pk_mul_f32 v[36:37], v[20:21], v[50:51] op_sel_hi:[1,0]
	v_pk_mul_f32 v[34:35], v[18:19], v[50:51] op_sel_hi:[1,0]
	v_pk_mul_f32 v[64:65], v[16:17], v[50:51] op_sel_hi:[1,0]
	v_pk_mul_f32 v[62:63], v[14:15], v[50:51] op_sel_hi:[1,0]
	v_pk_mul_f32 v[60:61], v[12:13], v[50:51] op_sel_hi:[1,0]
	v_pk_mul_f32 v[58:59], v[10:11], v[50:51] op_sel_hi:[1,0]
	v_pk_mul_f32 v[56:57], v[8:9], v[50:51] op_sel_hi:[1,0]
	v_pk_mul_f32 v[54:55], v[6:7], v[50:51] op_sel_hi:[1,0]
	v_pk_mul_f32 v[52:53], v[4:5], v[50:51] op_sel_hi:[1,0]
	v_pk_mul_f32 v[50:51], v[2:3], v[50:51] op_sel_hi:[1,0]
	v_cvt_pk_bf16_f32 v142, v142, v66
	v_cvt_pk_bf16_f32 v144, v87, v88
	v_cvt_pk_bf16_f32 v145, v89, v146
	v_cvt_pk_bf16_f32 v88, v165, v84
	v_cvt_pk_bf16_f32 v89, v170, v90
	v_cvt_pk_bf16_f32 v90, v91, v150
	v_cvt_pk_bf16_f32 v91, v151, v152
	v_cvt_pk_bf16_f32 v84, v153, v154
	ds_read_b64_tr_b16 v[150:151], v134
	v_cvt_pk_bf16_f32 v143, v85, v86
	v_cvt_pk_bf16_f32 v85, v155, v158
	ds_read_b64_tr_b16 v[152:153], v133
	ds_read_b64_tr_b16 v[154:155], v135
	v_cvt_pk_bf16_f32 v146, v147, v148
	v_cvt_pk_bf16_f32 v147, v149, v156
	v_cvt_pk_bf16_f32 v148, v157, v160
	ds_read_b64_tr_b16 v[156:157], v132
	s_waitcnt lgkmcnt(2)
	v_mfma_f32_32x32x16_bf16 v[34:49], v[150:153], v[142:145], v[34:49]
	v_cvt_pk_bf16_f32 v149, v161, v166
	v_cvt_pk_bf16_f32 v86, v159, v162
	v_cvt_pk_bf16_f32 v87, v163, v168
	s_mov_b64 s[74:75], 0
	s_waitcnt lgkmcnt(0)
	v_mfma_f32_32x32x16_bf16 v[50:65], v[154:157], v[142:145], v[50:65]
	ds_read_b64_tr_b16 v[142:143], v129
	ds_read_b64_tr_b16 v[144:145], v128
	ds_read_b64_tr_b16 v[150:151], v127
	ds_read_b64_tr_b16 v[152:153], v126
	s_waitcnt lgkmcnt(2)
	v_mfma_f32_32x32x16_bf16 v[34:49], v[142:145], v[146:149], v[34:49]
	ds_read_b64_tr_b16 v[142:143], v125
	ds_read_b64_tr_b16 v[144:145], v124
	s_waitcnt lgkmcnt(2)
	v_mfma_f32_32x32x16_bf16 v[50:65], v[150:153], v[146:149], v[50:65]
	ds_read_b64_tr_b16 v[146:147], v123
	ds_read_b64_tr_b16 v[148:149], v122
	s_waitcnt lgkmcnt(2)
	v_mfma_f32_32x32x16_bf16 v[34:49], v[142:145], v[88:91], v[34:49]
	s_waitcnt lgkmcnt(0)
	v_mfma_f32_32x32x16_bf16 v[50:65], v[146:149], v[88:91], v[50:65]
	ds_read_b64_tr_b16 v[88:89], v121
	ds_read_b64_tr_b16 v[90:91], v120
	ds_read_b64_tr_b16 v[142:143], v119
	ds_read_b64_tr_b16 v[144:145], v118
	s_waitcnt lgkmcnt(2)
	v_mfma_f32_32x32x16_bf16 v[34:49], v[88:91], v[84:87], v[34:49]
	s_waitcnt lgkmcnt(0)
	v_mfma_f32_32x32x16_bf16 v[50:65], v[142:145], v[84:87], v[50:65]

; #define LAS __attribute__((address_space(3)))
; #define WG_BAR() do { asm volatile("s_waitcnt lgkmcnt(0)" ::: "memory"); __builtin_amdgcn_s_barrier(); asm volatile("" ::: "memory"); } while (0)
; #define ATT_DMA(t) do { const int t_ = (t) < NS ? (t) : NS - 1; const size_t ro_ = (size_t)TILE_ROW(t_) * ZC; LAS unsigned char* d_ = dk0 + ((t) % ATT_NB) * KV_BUF; \
;         __builtin_amdgcn_global_load_lds((const unsigned*)(gk + ro_), (LAS unsigned*)d_, 16, 0, 0); __builtin_amdgcn_global_load_lds((const unsigned*)(gv + ro_), (LAS unsigned*)(d_ + KV_TILE), 16, 0, 0); } while (0)
; template <bool ISB>
; __device__ __forceinline__ void attn_wg_item(Frame& F, int l, int idx) {
;     ...
;     for (int s = 0; s < NS; ++s) {
;         ATT_DMA(s + ATT_D);
;         asm volatile("s_waitcnt vmcnt(8)" ::: "memory");
;         WG_BAR();
;         LAS unsigned char* cur = ring + (s % ATT_NB) * KV_BUF;
;         if (s >= nloc) { ScorePlain sf; attn_step(st, qf, cur, cur + KV_TILE, lane, sf); }
;         else if (!ISB) { int dkv = krow_base + 64 * s - qrow0; asm volatile("" : "+v"(dkv)); ScoreWin sf{dkv}; attn_step(st, qf, cur, cur + KV_TILE, lane, sf); }
;         else { const int gr = r0 + (w >> 1); int kr0 = gr - 4; kr0 = kr0 < 0 ? 0 : (kr0 > 120 ? 120 : kr0); const int kr = kmin + s;
;             if (kr >= kr0 && kr < kr0 + 8) { const int cq = 32 * (w & 1) + (lane & 31), hh = lane >> 5; int cs = cq - 8; cs = cs < 0 ? 0 : (cs > 48 ? 48 : cs);
;                 ScoreNb sf{(LAS unsigned char*)(tab + 64) + ((kr - gr + 7) * 31 + 15 - cq + 4 * hh) * 4, cs - 4 * hh}; attn_step(st, qf, cur, cur + KV_TILE, lane, sf); } }
;     }
.Lb623_exit:
	v_mov_b32_e32 v140, v131
	v_mov_b32_e32 v141, v130
	s_nop 8
	v_mov_b32_e32 v34, v18
	v_mov_b32_e32 v35, v19
	v_mov_b32_e32 v36, v20
	v_mov_b32_e32 v37, v21
	v_mov_b32_e32 v38, v22
	v_mov_b32_e32 v39, v23
	v_mov_b32_e32 v40, v24
	v_mov_b32_e32 v41, v25
	v_mov_b32_e32 v42, v26
	v_mov_b32_e32 v43, v27
	v_mov_b32_e32 v44, v28
	v_mov_b32_e32 v45, v29
	v_mov_b32_e32 v46, v30
	v_mov_b32_e32 v47, v31
	v_mov_b32_e32 v48, v32
	v_mov_b32_e32 v49, v33
	v_mov_b32_e32 v50, v2
	v_mov_b32_e32 v51, v3
	v_mov_b32_e32 v52, v4
	v_mov_b32_e32 v53, v5
	v_mov_b32_e32 v54, v6
	v_mov_b32_e32 v55, v7
	v_mov_b32_e32 v56, v8
	v_mov_b32_e32 v57, v9
	v_mov_b32_e32 v58, v10
	v_mov_b32_e32 v59, v11
	v_mov_b32_e32 v60, v12
	v_mov_b32_e32 v61, v13
	v_mov_b32_e32 v62, v14
	v_mov_b32_e32 v63, v15
	v_mov_b32_e32 v64, v16
	v_mov_b32_e32 v65, v17
	s_branch .LBB0_626
	s_nop 0
	s_nop 0
	s_nop 0
	s_nop 0
	s_nop 0
	s_nop 0
	s_nop 0
	s_nop 0
	s_nop 0
	s_nop 0
	s_nop 0
	s_nop 0
	s_nop 0
	s_nop 0
	s_nop 0
	s_nop 0
	s_nop 0
	s_nop 0
	s_nop 0
	s_nop 0
	s_nop 0
	s_nop 0
	s_nop 0
.LBB0_624:
	s_addk_i32 s81, 0x4000
	s_add_i32 s80, s80, 1
	s_add_i32 s1, s82, 1
	s_cmp_lg_u32 s82, s79
	v_add_u32_e32 v109, 0x7c, v109
	s_cbranch_scc0 .LBB0_626
	v_mov_b32_e32 v130, v141
	s_mov_b32 s82, s1
	v_mov_b32_e32 v131, v140
	s_nop 0
	v_pk_mov_b32 v[2:3], v[50:51], v[50:51] op_sel:[0,1]
	v_pk_mov_b32 v[4:5], v[52:53], v[52:53] op_sel:[0,1]
	v_pk_mov_b32 v[6:7], v[54:55], v[54:55] op_sel:[0,1]
	v_pk_mov_b32 v[8:9], v[56:57], v[56:57] op_sel:[0,1]
	v_pk_mov_b32 v[10:11], v[58:59], v[58:59] op_sel:[0,1]
	v_pk_mov_b32 v[12:13], v[60:61], v[60:61] op_sel:[0,1]
	v_pk_mov_b32 v[14:15], v[62:63], v[62:63] op_sel:[0,1]
	v_pk_mov_b32 v[16:17], v[64:65], v[64:65] op_sel:[0,1]
	v_pk_mov_b32 v[18:19], v[34:35], v[34:35] op_sel:[0,1]
	v_pk_mov_b32 v[20:21], v[36:37], v[36:37] op_sel:[0,1]
	v_pk_mov_b32 v[22:23], v[38:39], v[38:39] op_sel:[0,1]
	v_pk_mov_b32 v[24:25], v[40:41], v[40:41] op_sel:[0,1]
	v_pk_mov_b32 v[26:27], v[42:43], v[42:43] op_sel:[0,1]
	v_pk_mov_b32 v[28:29], v[44:45], v[44:45] op_sel:[0,1]
	v_pk_mov_b32 v[30:31], v[46:47], v[46:47] op_sel:[0,1]
	v_pk_mov_b32 v[32:33], v[48:49], v[48:49] op_sel:[0,1]
	s_branch .LBB0_618
